# k29 + mla_b phase visits items as it^512 (q_b tiles in round 1, kv_b tiles as the tail)
# baseline (speedup 1.0000x reference)
.LBB0_386:
	s_and_b64 vcc, exec, s[2:3]
	s_cbranch_vccz .LBB0_470
	s_cmp_gt_i32 s10, 0
	s_mov_b64 s[0:1], -1
	v_readlane_b32 s12, v255, 22
	s_cbranch_scc0 .LBB0_472
	v_readlane_b32 s0, v253, 56
	v_readlane_b32 s1, v253, 57
	s_andn2_b64 vcc, exec, s[0:1]
	s_cbranch_vccnz .LBB0_474
	s_lshl_b32 s1, s11, 20
	s_add_u32 s36, s34, s1
	s_addc_u32 s6, s35, 0
	s_add_u32 s2, s34, 0xb800000
	v_readlane_b32 s80, v253, 29
	s_addc_u32 s3, s35, 0
	s_lshl_b32 s1, s11, 10
	v_readlane_b32 s92, v253, 41
	v_readlane_b32 s82, v253, 31
	v_readlane_b32 s83, v253, 32
	v_readlane_b32 s86, v253, 35
	v_readlane_b32 s87, v253, 36
	v_readlane_b32 s88, v253, 37
	v_readlane_b32 s89, v253, 38
	v_readlane_b32 s90, v253, 39
	v_readlane_b32 s91, v253, 40
	v_readlane_b32 s93, v253, 42
	s_add_u32 s4, s92, s1
	v_readlane_b32 s90, v255, 12
	v_readlane_b32 s88, v255, 10
	v_readlane_b32 s86, v255, 8
	v_readlane_b32 s82, v255, 4
	s_addc_u32 s5, s93, 0
	v_readlane_b32 s91, v255, 13
	v_readlane_b32 s89, v255, 11
	v_readlane_b32 s87, v255, 9
	v_readlane_b32 s83, v255, 5
	v_writelane_b32 v255, s4, 43
	s_mul_i32 s1, s11, 0x120000
	s_mul_i32 s0, s11, 0x480000
	v_writelane_b32 v255, s5, 44
	s_mul_i32 s7, s11, 0xf00000
	v_readlane_b32 s4, v255, 20
	v_readlane_b32 s5, v255, 21
	s_add_u32 s4, s4, 0x6000000
	s_addc_u32 s5, s5, 0
	v_writelane_b32 v255, s4, 39
	v_readlane_b32 s40, v253, 1
	v_readlane_b32 s84, v253, 33
	v_writelane_b32 v255, s5, 40
	s_add_u32 s4, s34, 0xd700000
	s_addc_u32 s5, s35, 0
	v_writelane_b32 v255, s4, 41
	v_readlane_b32 s42, v253, 3
	v_readlane_b32 s85, v253, 34
	v_writelane_b32 v255, s5, 42
	s_add_u32 s4, s34, 0xa700000
	s_addc_u32 s5, s35, 0
	v_writelane_b32 v255, s4, 49
	v_readlane_b32 s43, v253, 4
	v_readlane_b32 s81, v253, 30
	v_writelane_b32 v255, s5, 50
	s_add_u32 s4, s34, s1
	s_addc_u32 s5, s35, 0
	s_add_u32 s4, s4, 0x1f00000
	s_addc_u32 s5, s5, 0
	v_writelane_b32 v255, s4, 51
	s_movk_i32 s81, 0x3ff
	s_movk_i32 s80, 0x400
	v_writelane_b32 v255, s5, 52
	s_add_u32 s4, s34, 0x2700000
	s_addc_u32 s5, s35, 0
	v_writelane_b32 v255, s4, 45
	v_readlane_b32 s94, v253, 43
	v_readlane_b32 s95, v253, 44
	v_writelane_b32 v255, s5, 46
	s_add_u32 s4, s34, 0x2720000
	s_addc_u32 s5, s35, 0
	v_writelane_b32 v255, s4, 47
	v_readlane_b32 s41, v253, 2
	s_nop 0
	v_writelane_b32 v255, s5, 48
	s_add_u32 s4, s34, 0xb700000
	s_addc_u32 s5, s35, 0
	s_add_u32 s22, s34, 0x3900000
	s_addc_u32 s23, s35, 0
	s_add_u32 s8, s34, s0
	s_addc_u32 s9, s35, 0
	s_add_u32 s46, s8, 0xad00000
	s_addc_u32 s47, s9, 0
	s_add_u32 s48, s34, 0x5100000
	s_addc_u32 s49, s35, 0
	s_add_u32 s7, s34, s7
	s_addc_u32 s8, s35, 0
	s_add_u32 s50, s7, 0xb900000
	s_addc_u32 s51, s8, 0
	v_readlane_b32 s8, v255, 23
	v_readlane_b32 s9, v255, 24
	s_add_u32 s1, s8, s1
	s_addc_u32 s7, s9, 0
	s_add_u32 s84, s42, s1
	s_addc_u32 s85, s43, s7
	s_add_u32 s0, s8, s0
	s_addc_u32 s1, s9, 0
	s_add_u32 s58, s42, s0
	s_addc_u32 s59, s43, s1
	s_mov_b64 s[42:43], 0x1000
	v_readlane_b32 s7, v253, 0
	s_xor_b32 s7, s7, 0x200
	s_branch .LBB0_392

.LBB0_391:
	v_readlane_b32 s0, v253, 24
	v_readlane_b32 s1, v253, 25
	s_load_dword s0, s[0:1], 0x0
	s_waitcnt lgkmcnt(0)
	s_xor_b32 s7, s7, 0x200
	s_add_i32 s7, s0, s7
	s_cmpk_gt_i32 s7, 0x3ff
	s_cbranch_scc1 .LBB0_474
	s_xor_b32 s7, s7, 0x200
